# start-up cg grid sync removed; barrier census reads its 16 counters with all loads in flight; gate-GEMM unit-transition drain removed
# speedup vs baseline: 1.0052x; 1.0040x over previous
.LBB0_263:
	s_add_u32 s82, s82, 0x80
	s_addc_u32 s83, s83, 0
	s_add_u32 vcc_lo, s84, 0x100
	v_mov_b32_e32 v0, 0
	s_addc_u32 vcc_hi, s85, 0
	s_mov_b32 s84, 0
	v_mov_b32_e32 v1, v0
	v_mov_b32_e32 v2, v0
	v_mov_b32_e32 v3, v0
	v_mov_b32_e32 v4, v0
	v_mov_b32_e32 v5, v0
	v_mov_b32_e32 v6, v0
	v_mov_b32_e32 v7, v0
	v_mov_b32_e32 v16, v0
	v_mov_b32_e32 v17, v0
	v_mov_b32_e32 v18, v0
	v_mov_b32_e32 v19, v0
	v_mov_b32_e32 v20, v0
	v_mov_b32_e32 v21, v0
	v_mov_b32_e32 v22, v0
	v_mov_b32_e32 v23, v0
	v_mov_b32_e32 v34, v0
	v_mov_b32_e32 v35, v0
	v_mov_b32_e32 v36, v0
	v_mov_b32_e32 v37, v0
	v_mov_b32_e32 v38, v0
	v_mov_b32_e32 v39, v0
	v_mov_b32_e32 v40, v0
	v_mov_b32_e32 v41, v0
	v_mov_b32_e32 v50, v0
	v_mov_b32_e32 v51, v0
	v_mov_b32_e32 v52, v0
	v_mov_b32_e32 v53, v0
	v_mov_b32_e32 v54, v0
	v_mov_b32_e32 v55, v0
	v_mov_b32_e32 v56, v0
	v_mov_b32_e32 v57, v0
	v_mov_b32_e32 v8, v0
	v_mov_b32_e32 v9, v0
	v_mov_b32_e32 v10, v0
	v_mov_b32_e32 v11, v0
	v_mov_b32_e32 v12, v0
	v_mov_b32_e32 v13, v0
	v_mov_b32_e32 v14, v0
	v_mov_b32_e32 v15, v0
	v_mov_b32_e32 v24, v0
	v_mov_b32_e32 v25, v0
	v_mov_b32_e32 v26, v0
	v_mov_b32_e32 v27, v0
	v_mov_b32_e32 v28, v0
	v_mov_b32_e32 v29, v0
	v_mov_b32_e32 v30, v0
	v_mov_b32_e32 v31, v0
	v_mov_b32_e32 v42, v0
	v_mov_b32_e32 v43, v0
	v_mov_b32_e32 v44, v0
	v_mov_b32_e32 v45, v0
	v_mov_b32_e32 v46, v0
	v_mov_b32_e32 v47, v0
	v_mov_b32_e32 v48, v0
	v_mov_b32_e32 v49, v0
	v_mov_b32_e32 v58, v0
	v_mov_b32_e32 v59, v0
	v_mov_b32_e32 v60, v0
	v_mov_b32_e32 v61, v0
	v_mov_b32_e32 v62, v0
	v_mov_b32_e32 v63, v0
	v_mov_b32_e32 v64, v0
	v_mov_b32_e32 v65, v0
	v_mov_b32_e32 v66, v0
	v_mov_b32_e32 v67, v0
	v_mov_b32_e32 v68, v0
	v_mov_b32_e32 v69, v0
	v_mov_b32_e32 v70, v0
	v_mov_b32_e32 v71, v0
	v_mov_b32_e32 v72, v0
	v_mov_b32_e32 v73, v0
	v_mov_b32_e32 v82, v0
	v_mov_b32_e32 v83, v0
	v_mov_b32_e32 v84, v0
	v_mov_b32_e32 v85, v0
	v_mov_b32_e32 v86, v0
	v_mov_b32_e32 v87, v0
	v_mov_b32_e32 v88, v0
	v_mov_b32_e32 v89, v0
	v_mov_b32_e32 v98, v0
	v_mov_b32_e32 v99, v0
	v_mov_b32_e32 v100, v0
	v_mov_b32_e32 v101, v0
	v_mov_b32_e32 v102, v0
	v_mov_b32_e32 v103, v0
	v_mov_b32_e32 v104, v0
	v_mov_b32_e32 v105, v0
	v_mov_b32_e32 v114, v0
	v_mov_b32_e32 v115, v0
	v_mov_b32_e32 v116, v0
	v_mov_b32_e32 v117, v0
	v_mov_b32_e32 v118, v0
	v_mov_b32_e32 v119, v0
	v_mov_b32_e32 v120, v0
	v_mov_b32_e32 v121, v0
	v_mov_b32_e32 v74, v0
	v_mov_b32_e32 v75, v0
	v_mov_b32_e32 v76, v0
	v_mov_b32_e32 v77, v0
	v_mov_b32_e32 v78, v0
	v_mov_b32_e32 v79, v0
	v_mov_b32_e32 v80, v0
	v_mov_b32_e32 v81, v0
	v_mov_b32_e32 v90, v0
	v_mov_b32_e32 v91, v0
	v_mov_b32_e32 v92, v0
	v_mov_b32_e32 v93, v0
	v_mov_b32_e32 v94, v0
	v_mov_b32_e32 v95, v0
	v_mov_b32_e32 v96, v0
	v_mov_b32_e32 v97, v0
	v_mov_b32_e32 v106, v0
	v_mov_b32_e32 v107, v0
	v_mov_b32_e32 v108, v0
	v_mov_b32_e32 v109, v0
	v_mov_b32_e32 v110, v0
	v_mov_b32_e32 v111, v0
	v_mov_b32_e32 v112, v0
	v_mov_b32_e32 v113, v0
	v_mov_b32_e32 v122, v0
	v_mov_b32_e32 v123, v0
	v_mov_b32_e32 v124, v0
	v_mov_b32_e32 v125, v0
	v_mov_b32_e32 v126, v0
	v_mov_b32_e32 v127, v0
	v_mov_b32_e32 v128, v0
	v_mov_b32_e32 v129, v0

.LBB0_369:
	s_waitcnt lgkmcnt(0)
	global_load_dword v1, v33, s[60:61] sc1
	global_load_dword v0, v33, s[60:61] offset:256 sc1
	global_load_dword v2, v33, s[60:61] offset:512 sc1
	global_load_dword v3, v33, s[60:61] offset:768 sc1
	global_load_dword v4, v33, s[60:61] offset:1024 sc1
	global_load_dword v5, v33, s[60:61] offset:1280 sc1
	global_load_dword v6, v33, s[60:61] offset:1536 sc1
	global_load_dword v7, v33, s[60:61] offset:1792 sc1
	global_load_dword v8, v33, s[60:61] offset:2048 sc1
	global_load_dword v9, v33, s[60:61] offset:2304 sc1
	global_load_dword v10, v33, s[60:61] offset:2560 sc1
	global_load_dword v11, v33, s[60:61] offset:2816 sc1
	global_load_dword v12, v33, s[60:61] offset:3072 sc1
	global_load_dword v13, v33, s[60:61] offset:3328 sc1
	global_load_dword v14, v33, s[60:61] offset:3584 sc1
	global_load_dword v15, v33, s[60:61] offset:3840 sc1
	s_mov_b64 s[42:43], -1
	s_mov_b64 s[44:45], -1
	s_waitcnt vmcnt(0)
	v_add_u32_e32 v16, v0, v1
	v_add_u32_e32 v16, v16, v2
	v_add_u32_e32 v16, v16, v3
	v_add_u32_e32 v16, v16, v4
	v_add_u32_e32 v16, v16, v5
	v_add_u32_e32 v16, v16, v6
	v_add_u32_e32 v16, v16, v7
	v_add_u32_e32 v16, v16, v8
	v_add_u32_e32 v16, v16, v9
	v_add_u32_e32 v16, v16, v10
	v_add_u32_e32 v16, v16, v11
	v_add_u32_e32 v16, v16, v12
	v_add_u32_e32 v16, v16, v13
	v_add_u32_e32 v16, v16, v14
	v_add_u32_e32 v16, v16, v15
	v_cmp_eq_u32_e32 vcc, s3, v16
	s_cbranch_vccnz .LBB0_368
	s_and_b32 s1, s0, 0xff
	s_cmp_eq_u32 s1, 0
	s_mov_b64 s[58:59], -1
	s_sleep 1
	s_cbranch_scc1 .LBB0_373
	s_and_b64 vcc, exec, s[58:59]
	s_cbranch_vccz .LBB0_368
